# speedup vs baseline: 1.0871x; 1.0871x over previous
; template <int DQK>
; __device__ __forceinline__ void attn_unit64(LAS char* lds, const bf16x8 (&qa)[DQK / 16], const bf16x8 (&qb)[DQK / 16],
;                                             const bf16_t* Kg, int ldk, const bf16_t* Vg, int ldv, int t0, int t1, bf16_t* Oga, int ogb_off) {
;     ...
;     u32x4 kreg0, kreg1 = (u32x4){0u, 0u, 0u, 0u}, vreg;
;     { const char* Kt = (const char*)(Kg + (size_t)t0 * 64 * ldk); const char* Vt = (const char*)(Vg + (size_t)t0 * 64 * ldv);
;       kreg0 = *(const u32x4*)(Kt + ksrc0); if (k2) kreg1 = *(const u32x4*)(Kt + ksrc1); vreg = *(const u32x4*)(Vt + vsrc); }
;     *(LAS u32x4*)(lds + kdst0) = kreg0; if (k2) *(LAS u32x4*)(lds + kdst1) = kreg1; *(LAS u32x4*)(lds + vdst) = vreg;
;     __syncthreads();
;     int cur = 0;
;     for (int t = t0; t < t1; ++t) {
;         const bool more = (t + 1 < t1);
;         if (more) { const char* Kt = (const char*)(Kg + (size_t)(t + 1) * 64 * ldk); const char* Vt = (const char*)(Vg + (size_t)(t + 1) * 64 * ldv);
;             kreg0 = *(const u32x4*)(Kt + ksrc0); if (k2) kreg1 = *(const u32x4*)(Kt + ksrc1); vreg = *(const u32x4*)(Vt + vsrc); }
;         const LAS char* kb = lds + cur * BUF + kfr; const LAS char* vb = lds + cur * BUF + vfr;
; #pragma nounroll
;         for (int kv = 0; kv < 2; ++kv) {
;             __builtin_amdgcn_iglp_opt(0);
;             f32x16 sa, sb;
; #pragma unroll
;             for (int i = 0; i < 16; ++i) { sa[i] = 0.f; sb[i] = 0.f; }
; #pragma unroll
;             for (int ds = 0; ds < DQK / 16; ++ds) {
;                 const bf16x8 kf = *(const LAS bf16x8*)(kb + kv * 32 * KP + ds * 32);
;                 sa = __builtin_amdgcn_mfma_f32_32x32x16_bf16(kf, qa[ds], sa, 0, 0, 0);
;                 sb = __builtin_amdgcn_mfma_f32_32x32x16_bf16(kf, qb[ds], sb, 0, 0, 0);
;             }
; #pragma unroll
;             for (int i = 0; i < 16; i += 2) { sa[i] = __builtin_amdgcn_exp2f(sa[i]); sa[i + 1] = __builtin_amdgcn_exp2f(sa[i + 1]); la0 += sa[i]; la1 += sa[i + 1];
;                                                sb[i] = __builtin_amdgcn_exp2f(sb[i]); sb[i + 1] = __builtin_amdgcn_exp2f(sb[i + 1]); lb0 += sb[i]; lb1 += sb[i + 1]; }
;             bf16x8 pa[2], pb[2]; pa[0] = pack8(sa, 0); pa[1] = pack8(sa, 1); pb[0] = pack8(sb, 0); pb[1] = pack8(sb, 1);
; #pragma unroll
;             for (int s2 = 0; s2 < 2; ++s2) {
;                 const int s = 2 * kv + s2;
.LBB0_1127:
	v_add_u32_e32 v238, v175, v176
	v_add_u32_e32 v239, v177, v178
	s_mov_b32 s98, 0
	s_movk_i32 s99, 0x5400
	s_mov_b32 s100, 0xa800
	s_add_i32 s101, s39, -1
	s_mov_b32 s4, 0
	ds_read_b128 v[182:185], v238
	ds_read_b128 v[186:189], v238 offset:32
	ds_read_b128 v[190:193], v238 offset:64
	ds_read_b128 v[194:197], v238 offset:96
	ds_read_b128 v[198:201], v238 offset:128
	ds_read_b128 v[202:205], v238 offset:160
	s_add_u32 s22, s18, 0x3000
	s_addc_u32 s23, s19, 0
	global_load_dwordx4 v[96:99], v160, s[22:23]
	s_cmp_eq_u64 s[0:1], 0
	s_cbranch_scc1 .Lp11_g1_pro
	global_load_dwordx4 v[100:103], v166, s[22:23]
.Lp11_g1_pro:
	s_mov_b32 s24, 0x2000
	s_mov_b32 s25, 0
	v_lshl_add_u64 v[180:181], v[168:169], 0, s[24:25]
	global_load_dwordx4 v[104:107], v[180:181], off
	v_mov_b32_e32 v240, v238
	v_add_u32_e32 v241, s99, v238
	v_mov_b32_e32 v242, v239
	v_add_u32_e32 v243, s99, v159
	v_add_u32_e32 v244, s99, v212
	v_add_u32_e32 v245, s99, v179
	v_mov_b32_e32 v64, 0xf149f2ca
	v_mov_b32_e32 v65, v64
	v_mov_b32_e32 v66, v64
	v_mov_b32_e32 v67, v64
	v_mov_b32_e32 v68, v64
	v_mov_b32_e32 v69, v64
	v_mov_b32_e32 v70, v64
	v_mov_b32_e32 v71, v64
	v_mov_b32_e32 v72, v64
	v_mov_b32_e32 v73, v64
	v_mov_b32_e32 v74, v64
	v_mov_b32_e32 v75, v64
	v_mov_b32_e32 v76, v64
	v_mov_b32_e32 v77, v64
	v_mov_b32_e32 v78, v64
	v_mov_b32_e32 v79, v64
	v_mov_b32_e32 v214, 0
	v_mov_b32_e32 v215, 0
	v_mov_b32_e32 v216, 0
	v_mov_b32_e32 v217, 0
	v_mov_b32_e32 v218, 0
	v_mov_b32_e32 v219, 0
	v_mov_b32_e32 v220, 0
	v_mov_b32_e32 v221, 0
	v_mov_b32_e32 v248, 0
	v_mov_b32_e32 v249, 0
	v_mov_b32_e32 v250, 0
	v_mov_b32_e32 v251, 0
	v_mov_b32_e32 v252, 0
	v_mov_b32_e32 v253, 0
	v_mov_b32_e32 v254, 0
	v_mov_b32_e32 v255, 0
.Lp11_loop:
	s_waitcnt lgkmcnt(0)
	v_mfma_f32_32x32x16_bf16 v[80:95], v[182:185], v[128:131], 0
	v_exp_f32_e32 v64, v64
	v_exp_f32_e32 v65, v65
	v_exp_f32_e32 v66, v66
	v_exp_f32_e32 v67, v67
	v_mfma_f32_32x32x16_bf16 v[80:95], v[186:189], v[124:127], v[80:95]
	v_exp_f32_e32 v68, v68
	v_exp_f32_e32 v69, v69
	v_cvt_pk_bf16_f32 v230, v64, v65
	v_cvt_pk_bf16_f32 v231, v66, v67
	v_mfma_f32_32x32x16_bf16 v[80:95], v[190:193], v[120:123], v[80:95]
	v_exp_f32_e32 v70, v70
	v_exp_f32_e32 v71, v71
	v_exp_f32_e32 v72, v72
	v_cvt_pk_bf16_f32 v232, v68, v69
	v_mfma_f32_32x32x16_bf16 v[80:95], v[194:197], v[116:119], v[80:95]
	v_exp_f32_e32 v73, v73
	v_exp_f32_e32 v74, v74
	v_cvt_pk_bf16_f32 v233, v70, v71
	v_exp_f32_e32 v75, v75
	v_mfma_f32_32x32x16_bf16 v[80:95], v[198:201], v[108:111], v[80:95]
	v_exp_f32_e32 v76, v76
	v_exp_f32_e32 v77, v77
	v_cvt_pk_bf16_f32 v234, v72, v73
	v_cvt_pk_bf16_f32 v235, v74, v75
	v_mfma_f32_32x32x16_bf16 v[80:95], v[202:205], v[112:115], v[80:95]
	v_exp_f32_e32 v78, v78
	v_exp_f32_e32 v79, v79
	v_cvt_pk_bf16_f32 v236, v76, v77
	v_cvt_pk_bf16_f32 v237, v78, v79
	v_mfma_f32_32x32x16_bf16 v[16:31], v[248:251], v[230:233], v[16:31]
	ds_read_b64_tr_b16 v[248:249], v242 offset:13312
	ds_read_b64_tr_b16 v[250:251], v242 offset:13824
	v_add_f32_e32 v172, v172, v64
	v_add_f32_e32 v173, v173, v65
	v_add_f32_e32 v172, v172, v66
	v_add_f32_e32 v173, v173, v67
	v_mfma_f32_32x32x16_bf16 v[0:15], v[252:255], v[230:233], v[0:15]
	ds_read_b64_tr_b16 v[252:253], v242 offset:17408
	ds_read_b64_tr_b16 v[254:255], v242 offset:17920
	v_add_f32_e32 v172, v172, v68
	v_add_f32_e32 v173, v173, v69
	v_add_f32_e32 v172, v172, v70
	v_add_f32_e32 v173, v173, v71
	v_mfma_f32_32x32x16_bf16 v[16:31], v[214:217], v[234:237], v[16:31]
	ds_read_b64_tr_b16 v[214:215], v242 offset:14336
	ds_read_b64_tr_b16 v[216:217], v242 offset:14848
	v_add_f32_e32 v172, v172, v72
	v_add_f32_e32 v173, v173, v73
	v_add_f32_e32 v172, v172, v74
	v_add_f32_e32 v173, v173, v75
	v_mfma_f32_32x32x16_bf16 v[0:15], v[218:221], v[234:237], v[0:15]
	ds_read_b64_tr_b16 v[218:219], v242 offset:18432
	ds_read_b64_tr_b16 v[220:221], v242 offset:18944
	v_add_f32_e32 v172, v172, v76
	v_add_f32_e32 v173, v173, v77
	v_add_f32_e32 v172, v172, v78
	v_add_f32_e32 v173, v173, v79
	v_mfma_f32_32x32x16_bf16 v[64:79], v[182:185], v[132:135], 0
	ds_read_b128 v[182:185], v240 offset:6656
	v_exp_f32_e32 v80, v80
	v_exp_f32_e32 v81, v81
	v_exp_f32_e32 v82, v82
	v_exp_f32_e32 v83, v83
	v_mfma_f32_32x32x16_bf16 v[64:79], v[186:189], v[136:139], v[64:79]
	ds_read_b128 v[186:189], v240 offset:6688
	v_exp_f32_e32 v84, v84
	v_exp_f32_e32 v85, v85
	v_cvt_pk_bf16_f32 v222, v80, v81
	v_cvt_pk_bf16_f32 v223, v82, v83
	v_mfma_f32_32x32x16_bf16 v[64:79], v[190:193], v[140:143], v[64:79]
	ds_read_b128 v[190:193], v240 offset:6720
	v_exp_f32_e32 v86, v86
	v_exp_f32_e32 v87, v87
	v_exp_f32_e32 v88, v88
	v_cvt_pk_bf16_f32 v224, v84, v85
	v_mfma_f32_32x32x16_bf16 v[64:79], v[194:197], v[144:147], v[64:79]
	ds_read_b128 v[194:197], v240 offset:6752
	v_exp_f32_e32 v89, v89
	v_exp_f32_e32 v90, v90
	v_cvt_pk_bf16_f32 v225, v86, v87
	v_exp_f32_e32 v91, v91
	v_mfma_f32_32x32x16_bf16 v[64:79], v[198:201], v[148:151], v[64:79]
	ds_read_b128 v[198:201], v240 offset:6784
	v_exp_f32_e32 v92, v92
	v_exp_f32_e32 v93, v93
	v_cvt_pk_bf16_f32 v226, v88, v89
	v_cvt_pk_bf16_f32 v227, v90, v91
	v_mfma_f32_32x32x16_bf16 v[64:79], v[202:205], v[152:155], v[64:79]
	ds_read_b128 v[202:205], v240 offset:6816
	v_exp_f32_e32 v94, v94
	v_exp_f32_e32 v95, v95
	v_cvt_pk_bf16_f32 v228, v92, v93
	v_cvt_pk_bf16_f32 v229, v94, v95
	s_waitcnt lgkmcnt(6)
	v_mfma_f32_32x32x16_bf16 v[32:47], v[248:251], v[222:225], v[32:47]
	v_add_f32_e32 v170, v170, v80
	v_add_f32_e32 v171, v171, v81
	v_add_f32_e32 v170, v170, v82
	v_add_f32_e32 v171, v171, v83
	s_waitcnt vmcnt(0)
	ds_write_b128 v243, v[96:99]
	s_cmp_eq_u64 s[0:1], 0
	v_mfma_f32_32x32x16_bf16 v[48:63], v[252:255], v[222:225], v[48:63]
	v_add_f32_e32 v170, v170, v84
	v_add_f32_e32 v171, v171, v85
	v_add_f32_e32 v170, v170, v86
	v_add_f32_e32 v171, v171, v87
	s_cbranch_scc1 .Lp11_w1_a
	ds_write_b128 v244, v[100:103]
; template <int DQK>
; __device__ __forceinline__ void attn_unit64(LAS char* lds, const bf16x8 (&qa)[DQK / 16], const bf16x8 (&qb)[DQK / 16],
;                                             const bf16_t* Kg, int ldk, const bf16_t* Vg, int ldv, int t0, int t1, bf16_t* Oga, int ogb_off) {
;     ...
;         if (more) { const char* Kt = (const char*)(Kg + (size_t)(t + 1) * 64 * ldk); const char* Vt = (const char*)(Vg + (size_t)(t + 1) * 64 * ldv);
;             kreg0 = *(const u32x4*)(Kt + ksrc0); if (k2) kreg1 = *(const u32x4*)(Kt + ksrc1); vreg = *(const u32x4*)(Vt + vsrc); }
;         const LAS char* kb = lds + cur * BUF + kfr; const LAS char* vb = lds + cur * BUF + vfr;
; #pragma nounroll
;         for (int kv = 0; kv < 2; ++kv) {
;             __builtin_amdgcn_iglp_opt(0);
;             f32x16 sa, sb;
; #pragma unroll
;             for (int i = 0; i < 16; ++i) { sa[i] = 0.f; sb[i] = 0.f; }
; #pragma unroll
;             for (int ds = 0; ds < DQK / 16; ++ds) {
;                 const bf16x8 kf = *(const LAS bf16x8*)(kb + kv * 32 * KP + ds * 32);
;                 sa = __builtin_amdgcn_mfma_f32_32x32x16_bf16(kf, qa[ds], sa, 0, 0, 0);
;                 sb = __builtin_amdgcn_mfma_f32_32x32x16_bf16(kf, qb[ds], sb, 0, 0, 0);
;             }
; #pragma unroll
;             for (int i = 0; i < 16; i += 2) { sa[i] = __builtin_amdgcn_exp2f(sa[i]); sa[i + 1] = __builtin_amdgcn_exp2f(sa[i + 1]); la0 += sa[i]; la1 += sa[i + 1];
;                                                sb[i] = __builtin_amdgcn_exp2f(sb[i]); sb[i + 1] = __builtin_amdgcn_exp2f(sb[i + 1]); lb0 += sb[i]; lb1 += sb[i + 1]; }
;             bf16x8 pa[2], pb[2]; pa[0] = pack8(sa, 0); pa[1] = pack8(sa, 1); pb[0] = pack8(sb, 0); pb[1] = pack8(sb, 1);
; #pragma unroll
;             for (int s2 = 0; s2 < 2; ++s2) {
;                 const int s = 2 * kv + s2;
;                 const s16x4 a0 = vtr(vb + (16 * s) * 64), a1 = vtr(vb + (16 * s + 8) * 64), c0 = vtr(vb + 4096 + (16 * s) * 64), c1 = vtr(vb + 4096 + (16 * s + 8) * 64);
;                 const bf16x8 va = (bf16x8){a0[0], a0[1], a0[2], a0[3], a1[0], a1[1], a1[2], a1[3]}, vc = (bf16x8){c0[0], c0[1], c0[2], c0[3], c1[0], c1[1], c1[2], c1[3]};
;                 oa0 = __builtin_amdgcn_mfma_f32_32x32x16_bf16(va, pa[s2], oa0, 0, 0, 0);
;                 oa1 = __builtin_amdgcn_mfma_f32_32x32x16_bf16(vc, pa[s2], oa1, 0, 0, 0);
.Lp11_w1_a:
	ds_write_b128 v245, v[104:107] offset:13312
	s_add_i32 s20, s4, 2
	s_min_u32 s20, s20, s101
	v_mfma_f32_32x32x16_bf16 v[32:47], v[214:217], v[226:229], v[32:47]
	v_add_f32_e32 v170, v170, v88
	v_add_f32_e32 v171, v171, v89
	v_add_f32_e32 v170, v170, v90
	v_add_f32_e32 v171, v171, v91
	s_mul_i32 s22, s20, 0x3000
	s_mul_hi_u32 s23, s20, 0x3000
	s_add_u32 s22, s18, s22
	s_addc_u32 s23, s19, s23
	s_lshl_b32 s24, s20, 13
	s_mov_b32 s25, 0
	v_lshl_add_u64 v[180:181], v[168:169], 0, s[24:25]
	v_mfma_f32_32x32x16_bf16 v[48:63], v[218:221], v[226:229], v[48:63]
	v_add_f32_e32 v170, v170, v92
	v_add_f32_e32 v171, v171, v93
	v_add_f32_e32 v170, v170, v94
	v_add_f32_e32 v171, v171, v95
	global_load_dwordx4 v[96:99], v160, s[22:23]
	s_cmp_eq_u64 s[0:1], 0
	s_cbranch_scc1 .Lp11_g1_a
	global_load_dwordx4 v[100:103], v166, s[22:23]
; template <int DQK>
; __device__ __forceinline__ void attn_unit64(LAS char* lds, const bf16x8 (&qa)[DQK / 16], const bf16x8 (&qb)[DQK / 16],
;                                             const bf16_t* Kg, int ldk, const bf16_t* Vg, int ldv, int t0, int t1, bf16_t* Oga, int ogb_off) {
;     ...
;         for (int kv = 0; kv < 2; ++kv) {
;             __builtin_amdgcn_iglp_opt(0);
;             f32x16 sa, sb;
; #pragma unroll
;             for (int i = 0; i < 16; ++i) { sa[i] = 0.f; sb[i] = 0.f; }
; #pragma unroll
;             for (int ds = 0; ds < DQK / 16; ++ds) {
;                 const bf16x8 kf = *(const LAS bf16x8*)(kb + kv * 32 * KP + ds * 32);
;                 sa = __builtin_amdgcn_mfma_f32_32x32x16_bf16(kf, qa[ds], sa, 0, 0, 0);
;                 sb = __builtin_amdgcn_mfma_f32_32x32x16_bf16(kf, qb[ds], sb, 0, 0, 0);
;             }
; #pragma unroll
;             for (int i = 0; i < 16; i += 2) { sa[i] = __builtin_amdgcn_exp2f(sa[i]); sa[i + 1] = __builtin_amdgcn_exp2f(sa[i + 1]); la0 += sa[i]; la1 += sa[i + 1];
;                                                sb[i] = __builtin_amdgcn_exp2f(sb[i]); sb[i + 1] = __builtin_amdgcn_exp2f(sb[i + 1]); lb0 += sb[i]; lb1 += sb[i + 1]; }
;             bf16x8 pa[2], pb[2]; pa[0] = pack8(sa, 0); pa[1] = pack8(sa, 1); pb[0] = pack8(sb, 0); pb[1] = pack8(sb, 1);
; #pragma unroll
;             for (int s2 = 0; s2 < 2; ++s2) {
;                 const int s = 2 * kv + s2;
;                 const s16x4 a0 = vtr(vb + (16 * s) * 64), a1 = vtr(vb + (16 * s + 8) * 64), c0 = vtr(vb + 4096 + (16 * s) * 64), c1 = vtr(vb + 4096 + (16 * s + 8) * 64);
;                 const bf16x8 va = (bf16x8){a0[0], a0[1], a0[2], a0[3], a1[0], a1[1], a1[2], a1[3]}, vc = (bf16x8){c0[0], c0[1], c0[2], c0[3], c1[0], c1[1], c1[2], c1[3]};
;                 oa0 = __builtin_amdgcn_mfma_f32_32x32x16_bf16(va, pa[s2], oa0, 0, 0, 0);
;                 oa1 = __builtin_amdgcn_mfma_f32_32x32x16_bf16(vc, pa[s2], oa1, 0, 0, 0);
;                 ob0 = __builtin_amdgcn_mfma_f32_32x32x16_bf16(va, pb[s2], ob0, 0, 0, 0);
;                 ob1 = __builtin_amdgcn_mfma_f32_32x32x16_bf16(vc, pb[s2], ob1, 0, 0, 0);
;             }
;         }
;         if (more) { const unsigned bo = (cur ^ 1) * BUF; *(LAS u32x4*)(lds + bo + kdst0) = kreg0; if (k2) *(LAS u32x4*)(lds + bo + kdst1) = kreg1; *(LAS u32x4*)(lds + bo + vdst) = vreg; }
;         __syncthreads();
.Lp11_g1_a:
	global_load_dwordx4 v[104:107], v[180:181], off
	s_waitcnt lgkmcnt(2)
	v_mfma_f32_32x32x16_bf16 v[80:95], v[182:185], v[128:131], 0
	v_exp_f32_e32 v64, v64
	v_exp_f32_e32 v65, v65
	v_exp_f32_e32 v66, v66
	v_exp_f32_e32 v67, v67
	v_mfma_f32_32x32x16_bf16 v[80:95], v[186:189], v[124:127], v[80:95]
	v_exp_f32_e32 v68, v68
	v_exp_f32_e32 v69, v69
	v_cvt_pk_bf16_f32 v230, v64, v65
	v_cvt_pk_bf16_f32 v231, v66, v67
	v_mfma_f32_32x32x16_bf16 v[80:95], v[190:193], v[120:123], v[80:95]
	v_exp_f32_e32 v70, v70
	v_exp_f32_e32 v71, v71
	v_exp_f32_e32 v72, v72
	v_cvt_pk_bf16_f32 v232, v68, v69
	v_mfma_f32_32x32x16_bf16 v[80:95], v[194:197], v[116:119], v[80:95]
	v_exp_f32_e32 v73, v73
	v_exp_f32_e32 v74, v74
	v_cvt_pk_bf16_f32 v233, v70, v71
	v_exp_f32_e32 v75, v75
	v_mfma_f32_32x32x16_bf16 v[80:95], v[198:201], v[108:111], v[80:95]
	v_exp_f32_e32 v76, v76
	v_exp_f32_e32 v77, v77
	v_cvt_pk_bf16_f32 v234, v72, v73
	v_cvt_pk_bf16_f32 v235, v74, v75
	v_mfma_f32_32x32x16_bf16 v[80:95], v[202:205], v[112:115], v[80:95]
	v_exp_f32_e32 v78, v78
	v_exp_f32_e32 v79, v79
	v_cvt_pk_bf16_f32 v236, v76, v77
	v_cvt_pk_bf16_f32 v237, v78, v79
	v_mfma_f32_32x32x16_bf16 v[16:31], v[248:251], v[230:233], v[16:31]
	ds_read_b64_tr_b16 v[248:249], v242 offset:15360
	ds_read_b64_tr_b16 v[250:251], v242 offset:15872
	v_add_f32_e32 v172, v172, v64
	v_add_f32_e32 v173, v173, v65
	v_add_f32_e32 v172, v172, v66
	v_add_f32_e32 v173, v173, v67
	v_mfma_f32_32x32x16_bf16 v[0:15], v[252:255], v[230:233], v[0:15]
	ds_read_b64_tr_b16 v[252:253], v242 offset:19456
	ds_read_b64_tr_b16 v[254:255], v242 offset:19968
	v_add_f32_e32 v172, v172, v68
	v_add_f32_e32 v173, v173, v69
	v_add_f32_e32 v172, v172, v70
	v_add_f32_e32 v173, v173, v71
	v_mfma_f32_32x32x16_bf16 v[16:31], v[214:217], v[234:237], v[16:31]
	ds_read_b64_tr_b16 v[214:215], v242 offset:16384
	ds_read_b64_tr_b16 v[216:217], v242 offset:16896
	v_add_f32_e32 v172, v172, v72
	v_add_f32_e32 v173, v173, v73
	v_add_f32_e32 v172, v172, v74
	v_add_f32_e32 v173, v173, v75
	v_mfma_f32_32x32x16_bf16 v[0:15], v[218:221], v[234:237], v[0:15]
	ds_read_b64_tr_b16 v[218:219], v242 offset:20480
	ds_read_b64_tr_b16 v[220:221], v242 offset:20992
	v_add_f32_e32 v172, v172, v76
	v_add_f32_e32 v173, v173, v77
	v_add_f32_e32 v172, v172, v78
	v_add_f32_e32 v173, v173, v79
	s_waitcnt lgkmcnt(8)
	s_barrier
	v_mfma_f32_32x32x16_bf16 v[64:79], v[182:185], v[132:135], 0
	ds_read_b128 v[182:185], v241
	v_exp_f32_e32 v80, v80
	v_exp_f32_e32 v81, v81
	v_exp_f32_e32 v82, v82
	v_exp_f32_e32 v83, v83
	v_mfma_f32_32x32x16_bf16 v[64:79], v[186:189], v[136:139], v[64:79]
	ds_read_b128 v[186:189], v241 offset:32
	v_exp_f32_e32 v84, v84
	v_exp_f32_e32 v85, v85
	v_cvt_pk_bf16_f32 v222, v80, v81
	v_cvt_pk_bf16_f32 v223, v82, v83
	v_mfma_f32_32x32x16_bf16 v[64:79], v[190:193], v[140:143], v[64:79]
	ds_read_b128 v[190:193], v241 offset:64
	v_exp_f32_e32 v86, v86
	v_exp_f32_e32 v87, v87
	v_exp_f32_e32 v88, v88
	v_cvt_pk_bf16_f32 v224, v84, v85
	v_mfma_f32_32x32x16_bf16 v[64:79], v[194:197], v[144:147], v[64:79]
	ds_read_b128 v[194:197], v241 offset:96
	v_exp_f32_e32 v89, v89
	v_exp_f32_e32 v90, v90
	v_cvt_pk_bf16_f32 v225, v86, v87
	v_exp_f32_e32 v91, v91
	v_mfma_f32_32x32x16_bf16 v[64:79], v[198:201], v[148:151], v[64:79]
	ds_read_b128 v[198:201], v241 offset:128
	v_exp_f32_e32 v92, v92
	v_exp_f32_e32 v93, v93
	v_cvt_pk_bf16_f32 v226, v88, v89
	v_cvt_pk_bf16_f32 v227, v90, v91
	v_mfma_f32_32x32x16_bf16 v[64:79], v[202:205], v[152:155], v[64:79]
	ds_read_b128 v[202:205], v241 offset:160
	v_exp_f32_e32 v94, v94
	v_exp_f32_e32 v95, v95
	v_cvt_pk_bf16_f32 v228, v92, v93
	v_cvt_pk_bf16_f32 v229, v94, v95
	s_waitcnt lgkmcnt(6)
	v_mfma_f32_32x32x16_bf16 v[32:47], v[248:251], v[222:225], v[32:47]
	v_add_f32_e32 v170, v170, v80
	v_add_f32_e32 v171, v171, v81
	v_add_f32_e32 v170, v170, v82
	v_add_f32_e32 v171, v171, v83
	v_mfma_f32_32x32x16_bf16 v[48:63], v[252:255], v[222:225], v[48:63]
	v_add_f32_e32 v170, v170, v84
	v_add_f32_e32 v171, v171, v85
	v_add_f32_e32 v170, v170, v86
	v_add_f32_e32 v171, v171, v87
	s_mov_b32 s20, s98
	s_mov_b32 s98, s99
	s_mov_b32 s99, s100
	s_mov_b32 s100, s20
	v_mfma_f32_32x32x16_bf16 v[32:47], v[214:217], v[226:229], v[32:47]
	v_add_f32_e32 v170, v170, v88
	v_add_f32_e32 v171, v171, v89
	v_add_f32_e32 v170, v170, v90
	v_add_f32_e32 v171, v171, v91
	v_add_u32_e32 v240, s98, v238
	v_add_u32_e32 v241, s99, v238
	v_add_u32_e32 v242, s98, v239
	v_mfma_f32_32x32x16_bf16 v[48:63], v[218:221], v[226:229], v[48:63]
	v_add_f32_e32 v170, v170, v92
	v_add_f32_e32 v171, v171, v93
	v_add_f32_e32 v170, v170, v94
	v_add_f32_e32 v171, v171, v95
	v_add_u32_e32 v243, s99, v159
	v_add_u32_e32 v244, s99, v212
	v_add_u32_e32 v245, s99, v179
	s_add_i32 s4, s4, 1
	s_cmp_lt_u32 s4, s39
	s_cbranch_scc1 .Lp11_loop
	v_exp_f32_e32 v64, v64
	v_exp_f32_e32 v65, v65
	v_exp_f32_e32 v66, v66
	v_exp_f32_e32 v67, v67
	v_exp_f32_e32 v68, v68
	v_exp_f32_e32 v69, v69
	v_cvt_pk_bf16_f32 v230, v64, v65
	v_cvt_pk_bf16_f32 v231, v66, v67
	v_exp_f32_e32 v70, v70
	v_exp_f32_e32 v71, v71
	v_exp_f32_e32 v72, v72
	v_cvt_pk_bf16_f32 v232, v68, v69
	v_exp_f32_e32 v73, v73
	v_exp_f32_e32 v74, v74
	v_cvt_pk_bf16_f32 v233, v70, v71
	v_exp_f32_e32 v75, v75
	v_exp_f32_e32 v76, v76
	v_exp_f32_e32 v77, v77
	v_cvt_pk_bf16_f32 v234, v72, v73
	v_cvt_pk_bf16_f32 v235, v74, v75
	v_exp_f32_e32 v78, v78
	v_exp_f32_e32 v79, v79
	v_cvt_pk_bf16_f32 v236, v76, v77
	v_cvt_pk_bf16_f32 v237, v78, v79
	v_add_f32_e32 v172, v172, v64
	v_add_f32_e32 v173, v173, v65
	v_add_f32_e32 v172, v172, v66
	v_add_f32_e32 v173, v173, v67
	v_add_f32_e32 v172, v172, v68
	v_add_f32_e32 v173, v173, v69
	v_add_f32_e32 v172, v172, v70
	v_add_f32_e32 v173, v173, v71
	v_add_f32_e32 v172, v172, v72
	v_add_f32_e32 v173, v173, v73
	v_add_f32_e32 v172, v172, v74
	v_add_f32_e32 v173, v173, v75
	v_add_f32_e32 v172, v172, v76
	v_add_f32_e32 v173, v173, v77
	v_add_f32_e32 v172, v172, v78
	v_add_f32_e32 v173, v173, v79
	s_nop 1
	v_mfma_f32_32x32x16_bf16 v[16:31], v[248:251], v[230:233], v[16:31]
	v_mfma_f32_32x32x16_bf16 v[0:15], v[252:255], v[230:233], v[0:15]
	v_mfma_f32_32x32x16_bf16 v[16:31], v[214:217], v[234:237], v[16:31]
	v_mfma_f32_32x32x16_bf16 v[0:15], v[218:221], v[234:237], v[0:15]
	s_waitcnt vmcnt(0)
	s_waitcnt lgkmcnt(0)
	s_barrier
	s_branch .LBB0_1115

; #define LAS __attribute__((address_space(3)))
; __global__ void __launch_bounds__(512) fwd_megakernel(Args args) {
;     extern __shared__ __attribute__((aligned(16))) unsigned char lds_raw[];
;     cg::grid_group grid = cg::this_grid();
;     LAS unsigned char* lds = (LAS unsigned char*)lds_raw;
	.amdhsa_kernel _Z14fwd_megakernel4Args
		.amdhsa_group_segment_fixed_size 0
		.amdhsa_private_segment_fixed_size 0
		.amdhsa_kernarg_size 456
		.amdhsa_user_sgpr_count 2
		.amdhsa_user_sgpr_dispatch_ptr 0
		.amdhsa_user_sgpr_queue_ptr 0
		.amdhsa_user_sgpr_kernarg_segment_ptr 1
		.amdhsa_user_sgpr_dispatch_id 0
		.amdhsa_user_sgpr_kernarg_preload_length 0
		.amdhsa_user_sgpr_kernarg_preload_offset 0
		.amdhsa_user_sgpr_private_segment_size 0
		.amdhsa_uses_dynamic_stack 0
		.amdhsa_enable_private_segment 0
		.amdhsa_system_sgpr_workgroup_id_x 1
		.amdhsa_system_sgpr_workgroup_id_y 0
		.amdhsa_system_sgpr_workgroup_id_z 0
		.amdhsa_system_sgpr_workgroup_info 0
		.amdhsa_system_vgpr_workitem_id 2
		.amdhsa_next_free_vgpr 256
		.amdhsa_next_free_sgpr 102
		.amdhsa_accum_offset 256
		.amdhsa_reserve_vcc 1
		.amdhsa_float_round_mode_32 0
		.amdhsa_float_round_mode_16_64 0
		.amdhsa_float_denorm_mode_32 3
		.amdhsa_float_denorm_mode_16_64 3
		.amdhsa_dx10_clamp 1
		.amdhsa_ieee_mode 1
		.amdhsa_fp16_overflow 0
		.amdhsa_tg_split 0
		.amdhsa_exception_fp_ieee_invalid_op 0
		.amdhsa_exception_fp_denorm_src 0
		.amdhsa_exception_fp_ieee_div_zero 0
		.amdhsa_exception_fp_ieee_overflow 0
		.amdhsa_exception_fp_ieee_underflow 0
		.amdhsa_exception_fp_ieee_inexact 0
		.amdhsa_exception_int_div_zero 0
	.end_amdhsa_kernel

; #define LAS __attribute__((address_space(3)))
; __global__ void __launch_bounds__(512) fwd_megakernel(Args args) {
;     extern __shared__ __attribute__((aligned(16))) unsigned char lds_raw[];
;     cg::grid_group grid = cg::this_grid();
;     LAS unsigned char* lds = (LAS unsigned char*)lds_raw;
amdhsa.kernels:
  - .agpr_count:     0
    .args:
      - .offset:         0
        .size:           200
        .value_kind:     by_value
      - .offset:         200
        .size:           4
        .value_kind:     hidden_block_count_x
      - .offset:         204
        .size:           4
        .value_kind:     hidden_block_count_y
      - .offset:         208
        .size:           4
        .value_kind:     hidden_block_count_z
      - .offset:         212
        .size:           2
        .value_kind:     hidden_group_size_x
      - .offset:         214
        .size:           2
        .value_kind:     hidden_group_size_y
      - .offset:         216
        .size:           2
        .value_kind:     hidden_group_size_z
      - .offset:         218
        .size:           2
        .value_kind:     hidden_remainder_x
      - .offset:         220
        .size:           2
        .value_kind:     hidden_remainder_y
      - .offset:         222
        .size:           2
        .value_kind:     hidden_remainder_z
      - .offset:         240
        .size:           8
        .value_kind:     hidden_global_offset_x
      - .offset:         248
        .size:           8
        .value_kind:     hidden_global_offset_y
      - .offset:         256
        .size:           8
        .value_kind:     hidden_global_offset_z
      - .offset:         264
        .size:           2
        .value_kind:     hidden_grid_dims
      - .offset:         288
        .size:           8
        .value_kind:     hidden_multigrid_sync_arg
      - .offset:         320
        .size:           4
        .value_kind:     hidden_dynamic_lds_size
    .group_segment_fixed_size: 0
    .kernarg_segment_align: 8
    .kernarg_segment_size: 456
    .language:       OpenCL C
    .language_version:
      - 2
      - 0
    .max_flat_workgroup_size: 512
    .name:           _Z14fwd_megakernel4Args
    .private_segment_fixed_size: 0
    .sgpr_count:     108
    .sgpr_spill_count: 90
    .symbol:         _Z14fwd_megakernel4Args.kd
    .uniform_work_group_size: 1
    .uses_dynamic_stack: false
    .vgpr_count:     256
    .vgpr_spill_count: 0
    .wavefront_size: 64
